# GEMM K-loop priority toggles inverted (raised during the load segments, lowered during the MFMA blocks)
# speedup vs baseline: 1.0016x; 1.0011x over previous
.LBB0_463:
	v_or_b32_e32 v136, 0x10000, v238
	v_add_u32_e32 v140, 0x10400, v238
	v_add_u32_e32 v144, 0x10800, v238
	v_add_u32_e32 v148, 0x10c00, v238
	v_or_b32_e32 v152, 0x14000, v238
	v_add_u32_e32 v156, 0x14400, v238
	v_add_u32_e32 v160, 0x14800, v238
	v_add_u32_e32 v164, 0x14c00, v238
	s_add_i32 s9, s6, 2
	s_waitcnt lgkmcnt(0)
	ds_read_b128 v[136:139], v136
	ds_read_b128 v[140:143], v140
	ds_read_b128 v[144:147], v144
	ds_read_b128 v[148:151], v148
	ds_read_b128 v[152:155], v152
	ds_read_b128 v[156:159], v156
	ds_read_b128 v[160:163], v160
	ds_read_b128 v[164:167], v164
	s_add_u32 s10, s4, 0x80
	s_addc_u32 s7, s5, 0
	s_cmp_eq_u32 s94, s6
	s_cselect_b32 s6, s62, s10
	s_cselect_b32 s7, s63, s7
	s_cselect_b32 s11, s65, s8
	s_cselect_b32 s10, s64, s3
	v_lshl_add_u64 v[172:173], s[4:5], 0, v[182:183]
	s_add_i32 m0, s35, 0xc000
	ds_read_b128 v[168:171], v237
	ds_read_b128 v[186:189], v237 offset:1024
	ds_read_b128 v[190:193], v237 offset:2048
	ds_read_b128 v[194:197], v237 offset:3072
	ds_read_b128 v[198:201], v237 offset:4096
	ds_read_b128 v[202:205], v237 offset:5120
	ds_read_b128 v[206:209], v237 offset:6144
	ds_read_b128 v[240:243], v237 offset:7168
	global_load_lds_dwordx4 v[172:173], off
	v_lshl_add_u64 v[172:173], s[4:5], 0, v[184:185]
	s_add_i32 m0, s35, 0xe000
	s_nop 0
	global_load_lds_dwordx4 v[172:173], off
	s_waitcnt vmcnt(8)
	s_waitcnt lgkmcnt(0)
	s_barrier
	s_setprio 0
	s_waitcnt lgkmcnt(0)
	v_mfma_f32_16x16x32_bf16 v[132:135], v[136:139], v[168:171], v[132:135]
	v_mfma_f32_16x16x32_bf16 v[128:131], v[144:147], v[168:171], v[128:131]
	v_mfma_f32_16x16x32_bf16 v[116:119], v[136:139], v[190:193], v[116:119]
	v_mfma_f32_16x16x32_bf16 v[106:109], v[144:147], v[190:193], v[106:109]
	v_mfma_f32_16x16x32_bf16 v[94:97], v[136:139], v[198:201], v[94:97]
	v_mfma_f32_16x16x32_bf16 v[90:93], v[144:147], v[198:201], v[90:93]
	v_mfma_f32_16x16x32_bf16 v[78:81], v[136:139], v[206:209], v[78:81]
	v_mfma_f32_16x16x32_bf16 v[74:77], v[144:147], v[206:209], v[74:77]
	v_mfma_f32_16x16x32_bf16 v[132:135], v[140:143], v[186:189], v[132:135]
	v_mfma_f32_16x16x32_bf16 v[128:131], v[148:151], v[186:189], v[128:131]
	v_mfma_f32_16x16x32_bf16 v[116:119], v[140:143], v[194:197], v[116:119]
	v_mfma_f32_16x16x32_bf16 v[106:109], v[148:151], v[194:197], v[106:109]
	v_mfma_f32_16x16x32_bf16 v[94:97], v[140:143], v[202:205], v[94:97]
	v_mfma_f32_16x16x32_bf16 v[90:93], v[148:151], v[202:205], v[90:93]
	v_mfma_f32_16x16x32_bf16 v[78:81], v[140:143], v[240:243], v[78:81]
	v_mfma_f32_16x16x32_bf16 v[74:77], v[148:151], v[240:243], v[74:77]
	s_setprio 1
	s_setprio 0
	v_mfma_f32_16x16x32_bf16 v[124:127], v[152:155], v[168:171], v[124:127]
	v_mfma_f32_16x16x32_bf16 v[120:123], v[160:163], v[168:171], v[120:123]
	v_mfma_f32_16x16x32_bf16 v[102:105], v[152:155], v[190:193], v[102:105]
	v_mfma_f32_16x16x32_bf16 v[98:101], v[160:163], v[190:193], v[98:101]
	v_mfma_f32_16x16x32_bf16 v[86:89], v[152:155], v[198:201], v[86:89]
	v_mfma_f32_16x16x32_bf16 v[82:85], v[160:163], v[198:201], v[82:85]
	v_mfma_f32_16x16x32_bf16 v[70:73], v[152:155], v[206:209], v[70:73]
	v_mfma_f32_16x16x32_bf16 v[66:69], v[160:163], v[206:209], v[66:69]
	v_mfma_f32_16x16x32_bf16 v[124:127], v[156:159], v[186:189], v[124:127]
	v_mfma_f32_16x16x32_bf16 v[120:123], v[164:167], v[186:189], v[120:123]
	v_mfma_f32_16x16x32_bf16 v[102:105], v[156:159], v[194:197], v[102:105]
	v_mfma_f32_16x16x32_bf16 v[98:101], v[164:167], v[194:197], v[98:101]
	v_mfma_f32_16x16x32_bf16 v[86:89], v[156:159], v[202:205], v[86:89]
	v_mfma_f32_16x16x32_bf16 v[82:85], v[164:167], v[202:205], v[82:85]
	v_mfma_f32_16x16x32_bf16 v[70:73], v[156:159], v[240:243], v[70:73]
	v_mfma_f32_16x16x32_bf16 v[66:69], v[164:167], v[240:243], v[66:69]
	s_setprio 1
	s_barrier
	s_mov_b32 m0, s78
	v_lshl_add_u64 v[172:173], s[10:11], 0, v[180:181]
	v_lshl_add_u64 v[210:211], s[10:11], 0, v[176:177]
	s_add_u32 s10, s10, s24
	ds_read_b128 v[168:171], v237 offset:16384
	ds_read_b128 v[186:189], v237 offset:17408
	ds_read_b128 v[190:193], v237 offset:18432
	ds_read_b128 v[194:197], v237 offset:19456
	ds_read_b128 v[198:201], v237 offset:20480
	ds_read_b128 v[202:205], v237 offset:21504
	ds_read_b128 v[206:209], v237 offset:22528
	ds_read_b128 v[240:243], v237 offset:23552
	global_load_lds_dwordx4 v[172:173], off
	s_mov_b32 m0, s79
	s_addc_u32 s11, s11, s25
	global_load_lds_dwordx4 v[210:211], off
	v_lshl_add_u64 v[244:245], s[10:11], 0, v[180:181]
	s_mov_b32 m0, s80
	v_lshl_add_u64 v[246:247], s[10:11], 0, v[176:177]
	global_load_lds_dwordx4 v[244:245], off
	s_mov_b32 m0, s81
	v_lshl_add_u64 v[248:249], s[6:7], 0, v[178:179]
	global_load_lds_dwordx4 v[246:247], off
	s_mov_b32 m0, s35
	v_lshl_add_u64 v[250:251], s[6:7], 0, v[110:111]
	global_load_lds_dwordx4 v[248:249], off
	s_mov_b32 m0, s82
	s_nop 0
	global_load_lds_dwordx4 v[250:251], off
	s_waitcnt vmcnt(8)
	s_waitcnt lgkmcnt(0)
	s_barrier
	s_setprio 0
	s_waitcnt lgkmcnt(0)
	v_mfma_f32_16x16x32_bf16 v[62:65], v[136:139], v[168:171], v[62:65]
	v_mfma_f32_16x16x32_bf16 v[58:61], v[144:147], v[168:171], v[58:61]
	v_mfma_f32_16x16x32_bf16 v[46:49], v[136:139], v[190:193], v[46:49]
	v_mfma_f32_16x16x32_bf16 v[42:45], v[144:147], v[190:193], v[42:45]
	v_mfma_f32_16x16x32_bf16 v[30:33], v[136:139], v[198:201], v[30:33]
	v_mfma_f32_16x16x32_bf16 v[26:29], v[144:147], v[198:201], v[26:29]
	v_mfma_f32_16x16x32_bf16 v[14:17], v[136:139], v[206:209], v[14:17]
	v_mfma_f32_16x16x32_bf16 v[10:13], v[144:147], v[206:209], v[10:13]
	v_mfma_f32_16x16x32_bf16 v[62:65], v[140:143], v[186:189], v[62:65]
	v_mfma_f32_16x16x32_bf16 v[58:61], v[148:151], v[186:189], v[58:61]
	v_mfma_f32_16x16x32_bf16 v[46:49], v[140:143], v[194:197], v[46:49]
	v_mfma_f32_16x16x32_bf16 v[42:45], v[148:151], v[194:197], v[42:45]
	v_mfma_f32_16x16x32_bf16 v[30:33], v[140:143], v[202:205], v[30:33]
	v_mfma_f32_16x16x32_bf16 v[26:29], v[148:151], v[202:205], v[26:29]
	v_mfma_f32_16x16x32_bf16 v[14:17], v[140:143], v[240:243], v[14:17]
	v_mfma_f32_16x16x32_bf16 v[10:13], v[148:151], v[240:243], v[10:13]
	s_setprio 1
	s_setprio 0
	v_mfma_f32_16x16x32_bf16 v[54:57], v[152:155], v[168:171], v[54:57]
	v_mfma_f32_16x16x32_bf16 v[50:53], v[160:163], v[168:171], v[50:53]
	v_mfma_f32_16x16x32_bf16 v[38:41], v[152:155], v[190:193], v[38:41]
	v_mfma_f32_16x16x32_bf16 v[34:37], v[160:163], v[190:193], v[34:37]
	v_mfma_f32_16x16x32_bf16 v[22:25], v[152:155], v[198:201], v[22:25]
	v_mfma_f32_16x16x32_bf16 v[18:21], v[160:163], v[198:201], v[18:21]
	v_mfma_f32_16x16x32_bf16 v[6:9], v[152:155], v[206:209], v[6:9]
	v_mfma_f32_16x16x32_bf16 v[2:5], v[160:163], v[206:209], v[2:5]
	v_mfma_f32_16x16x32_bf16 v[54:57], v[156:159], v[186:189], v[54:57]
	v_mfma_f32_16x16x32_bf16 v[50:53], v[164:167], v[186:189], v[50:53]
	v_mfma_f32_16x16x32_bf16 v[38:41], v[156:159], v[194:197], v[38:41]
	v_mfma_f32_16x16x32_bf16 v[34:37], v[164:167], v[194:197], v[34:37]
	v_mfma_f32_16x16x32_bf16 v[22:25], v[156:159], v[202:205], v[22:25]
	v_mfma_f32_16x16x32_bf16 v[18:21], v[164:167], v[202:205], v[18:21]
	v_mfma_f32_16x16x32_bf16 v[6:9], v[156:159], v[240:243], v[6:9]
	v_mfma_f32_16x16x32_bf16 v[2:5], v[164:167], v[240:243], v[2:5]
	s_setprio 1
	s_barrier
	v_or_b32_e32 v136, 0x18000, v238
	v_add_u32_e32 v140, 0x18400, v238
	v_add_u32_e32 v144, 0x18800, v238
	v_add_u32_e32 v148, 0x18c00, v238
	v_or_b32_e32 v152, 0x1c000, v238
	v_add_u32_e32 v156, 0x1c400, v238
	v_add_u32_e32 v160, 0x1c800, v238
	v_add_u32_e32 v164, 0x1cc00, v238
	ds_read_b128 v[136:139], v136
	ds_read_b128 v[140:143], v140
	ds_read_b128 v[144:147], v144
	ds_read_b128 v[148:151], v148
	ds_read_b128 v[152:155], v152
	ds_read_b128 v[156:159], v156
	ds_read_b128 v[160:163], v160
	ds_read_b128 v[164:167], v164
	s_add_u32 s6, s6, s26
	s_addc_u32 s7, s7, s27
	s_mov_b32 m0, s83
	v_lshl_add_u64 v[212:213], s[6:7], 0, v[178:179]
	ds_read_b128 v[168:171], v237 offset:32768
	ds_read_b128 v[186:189], v237 offset:33792
	ds_read_b128 v[190:193], v237 offset:34816
	ds_read_b128 v[194:197], v237 offset:35840
	ds_read_b128 v[198:201], v237 offset:36864
	ds_read_b128 v[202:205], v237 offset:37888
	ds_read_b128 v[206:209], v237 offset:38912
	ds_read_b128 v[240:243], v237 offset:39936
	global_load_lds_dwordx4 v[212:213], off
	v_lshl_add_u64 v[212:213], s[6:7], 0, v[110:111]
	s_mov_b32 m0, s84
	s_nop 0
	global_load_lds_dwordx4 v[212:213], off
	s_waitcnt vmcnt(8)
	s_waitcnt lgkmcnt(0)
	s_barrier
	s_setprio 0
	s_waitcnt lgkmcnt(0)
	v_mfma_f32_16x16x32_bf16 v[132:135], v[136:139], v[168:171], v[132:135]
	v_mfma_f32_16x16x32_bf16 v[128:131], v[144:147], v[168:171], v[128:131]
	v_mfma_f32_16x16x32_bf16 v[116:119], v[136:139], v[190:193], v[116:119]
	v_mfma_f32_16x16x32_bf16 v[106:109], v[144:147], v[190:193], v[106:109]
	v_mfma_f32_16x16x32_bf16 v[94:97], v[136:139], v[198:201], v[94:97]
	v_mfma_f32_16x16x32_bf16 v[90:93], v[144:147], v[198:201], v[90:93]
	v_mfma_f32_16x16x32_bf16 v[78:81], v[136:139], v[206:209], v[78:81]
	v_mfma_f32_16x16x32_bf16 v[74:77], v[144:147], v[206:209], v[74:77]
	v_mfma_f32_16x16x32_bf16 v[132:135], v[140:143], v[186:189], v[132:135]
	v_mfma_f32_16x16x32_bf16 v[128:131], v[148:151], v[186:189], v[128:131]
	v_mfma_f32_16x16x32_bf16 v[116:119], v[140:143], v[194:197], v[116:119]
	v_mfma_f32_16x16x32_bf16 v[106:109], v[148:151], v[194:197], v[106:109]
	v_mfma_f32_16x16x32_bf16 v[94:97], v[140:143], v[202:205], v[94:97]
	v_mfma_f32_16x16x32_bf16 v[90:93], v[148:151], v[202:205], v[90:93]
	v_mfma_f32_16x16x32_bf16 v[78:81], v[140:143], v[240:243], v[78:81]
	v_mfma_f32_16x16x32_bf16 v[74:77], v[148:151], v[240:243], v[74:77]
	s_setprio 1
	s_setprio 0
	v_mfma_f32_16x16x32_bf16 v[124:127], v[152:155], v[168:171], v[124:127]
	v_mfma_f32_16x16x32_bf16 v[120:123], v[160:163], v[168:171], v[120:123]
	v_mfma_f32_16x16x32_bf16 v[102:105], v[152:155], v[190:193], v[102:105]
	v_mfma_f32_16x16x32_bf16 v[98:101], v[160:163], v[190:193], v[98:101]
	v_mfma_f32_16x16x32_bf16 v[86:89], v[152:155], v[198:201], v[86:89]
	v_mfma_f32_16x16x32_bf16 v[82:85], v[160:163], v[198:201], v[82:85]
	v_mfma_f32_16x16x32_bf16 v[70:73], v[152:155], v[206:209], v[70:73]
	v_mfma_f32_16x16x32_bf16 v[66:69], v[160:163], v[206:209], v[66:69]
	v_mfma_f32_16x16x32_bf16 v[124:127], v[156:159], v[186:189], v[124:127]
	v_mfma_f32_16x16x32_bf16 v[120:123], v[164:167], v[186:189], v[120:123]
	v_mfma_f32_16x16x32_bf16 v[102:105], v[156:159], v[194:197], v[102:105]
	v_mfma_f32_16x16x32_bf16 v[98:101], v[164:167], v[194:197], v[98:101]
	v_mfma_f32_16x16x32_bf16 v[86:89], v[156:159], v[202:205], v[86:89]
	v_mfma_f32_16x16x32_bf16 v[82:85], v[164:167], v[202:205], v[82:85]
	v_mfma_f32_16x16x32_bf16 v[70:73], v[156:159], v[240:243], v[70:73]
	v_mfma_f32_16x16x32_bf16 v[66:69], v[164:167], v[240:243], v[66:69]
	s_setprio 1
	s_barrier
	s_mov_b32 m0, s88
	v_lshl_add_u64 v[172:173], v[172:173], 0, s[0:1]
	ds_read_b128 v[168:171], v237 offset:49152
	ds_read_b128 v[186:189], v237 offset:50176
	ds_read_b128 v[190:193], v237 offset:51200
	ds_read_b128 v[194:197], v237 offset:52224
	ds_read_b128 v[198:201], v237 offset:53248
	ds_read_b128 v[202:205], v237 offset:54272
	ds_read_b128 v[206:209], v237 offset:55296
	ds_read_b128 v[240:243], v237 offset:56320
	global_load_lds_dwordx4 v[172:173], off
	v_lshl_add_u64 v[172:173], v[210:211], 0, s[0:1]
	s_mov_b32 m0, s89
	s_nop 0
	global_load_lds_dwordx4 v[172:173], off
	v_lshl_add_u64 v[172:173], v[244:245], 0, s[0:1]
	s_mov_b32 m0, s92
	s_nop 0
	global_load_lds_dwordx4 v[172:173], off
	v_lshl_add_u64 v[172:173], v[246:247], 0, s[0:1]
	s_mov_b32 m0, s93
	s_nop 0
	global_load_lds_dwordx4 v[172:173], off
	v_lshl_add_u64 v[172:173], v[248:249], 0, s[0:1]
	s_mov_b32 m0, s90
	s_nop 0
	global_load_lds_dwordx4 v[172:173], off
	v_lshl_add_u64 v[172:173], v[250:251], 0, s[0:1]
	s_mov_b32 m0, s91
	s_nop 0
	global_load_lds_dwordx4 v[172:173], off
	s_waitcnt vmcnt(8)
	s_waitcnt lgkmcnt(0)
	s_barrier
	s_setprio 0
	s_waitcnt lgkmcnt(0)
	v_mfma_f32_16x16x32_bf16 v[62:65], v[136:139], v[168:171], v[62:65]
	v_mfma_f32_16x16x32_bf16 v[58:61], v[144:147], v[168:171], v[58:61]
	v_mfma_f32_16x16x32_bf16 v[46:49], v[136:139], v[190:193], v[46:49]
	v_mfma_f32_16x16x32_bf16 v[42:45], v[144:147], v[190:193], v[42:45]
	v_mfma_f32_16x16x32_bf16 v[30:33], v[136:139], v[198:201], v[30:33]
	v_mfma_f32_16x16x32_bf16 v[26:29], v[144:147], v[198:201], v[26:29]
	v_mfma_f32_16x16x32_bf16 v[14:17], v[136:139], v[206:209], v[14:17]
	v_mfma_f32_16x16x32_bf16 v[10:13], v[144:147], v[206:209], v[10:13]
	v_mfma_f32_16x16x32_bf16 v[62:65], v[140:143], v[186:189], v[62:65]
	v_mfma_f32_16x16x32_bf16 v[58:61], v[148:151], v[186:189], v[58:61]
	v_mfma_f32_16x16x32_bf16 v[46:49], v[140:143], v[194:197], v[46:49]
	v_mfma_f32_16x16x32_bf16 v[42:45], v[148:151], v[194:197], v[42:45]
	v_mfma_f32_16x16x32_bf16 v[30:33], v[140:143], v[202:205], v[30:33]
	v_mfma_f32_16x16x32_bf16 v[26:29], v[148:151], v[202:205], v[26:29]
	v_mfma_f32_16x16x32_bf16 v[14:17], v[140:143], v[240:243], v[14:17]
	v_mfma_f32_16x16x32_bf16 v[10:13], v[148:151], v[240:243], v[10:13]
	s_setprio 1
	s_setprio 0
	v_mfma_f32_16x16x32_bf16 v[54:57], v[152:155], v[168:171], v[54:57]
	v_mfma_f32_16x16x32_bf16 v[50:53], v[160:163], v[168:171], v[50:53]
	v_mfma_f32_16x16x32_bf16 v[38:41], v[152:155], v[190:193], v[38:41]
	v_mfma_f32_16x16x32_bf16 v[34:37], v[160:163], v[190:193], v[34:37]
	v_mfma_f32_16x16x32_bf16 v[22:25], v[152:155], v[198:201], v[22:25]
	v_mfma_f32_16x16x32_bf16 v[18:21], v[160:163], v[198:201], v[18:21]
	v_mfma_f32_16x16x32_bf16 v[6:9], v[152:155], v[206:209], v[6:9]
	v_mfma_f32_16x16x32_bf16 v[2:5], v[160:163], v[206:209], v[2:5]
	v_mfma_f32_16x16x32_bf16 v[54:57], v[156:159], v[186:189], v[54:57]
	v_mfma_f32_16x16x32_bf16 v[50:53], v[164:167], v[186:189], v[50:53]
	v_mfma_f32_16x16x32_bf16 v[38:41], v[156:159], v[194:197], v[38:41]
	v_mfma_f32_16x16x32_bf16 v[34:37], v[164:167], v[194:197], v[34:37]
	v_mfma_f32_16x16x32_bf16 v[22:25], v[156:159], v[202:205], v[22:25]
	v_mfma_f32_16x16x32_bf16 v[18:21], v[164:167], v[202:205], v[18:21]
	v_mfma_f32_16x16x32_bf16 v[6:9], v[156:159], v[240:243], v[6:9]
	v_mfma_f32_16x16x32_bf16 v[2:5], v[164:167], v[240:243], v[2:5]
	s_setprio 1
	s_barrier
	s_add_u32 s4, s4, 0x100
	s_addc_u32 s5, s5, 0
	s_add_u32 s3, s3, 0x100
	s_addc_u32 s8, s8, 0
	s_cmp_ge_u32 s9, s85
	s_mov_b32 s6, s9
	s_cbranch_scc0 .LBB0_463
	s_and_b64 vcc, exec, s[58:59]
	s_cbranch_vccz .LBB0_466
	s_barrier
